# XCD barrier: first workgroup of each XCD to arrive starts an early L2 write-back so the leader's release write-back finds a mostly clean L2
# speedup vs baseline: 1.0009x; 1.0009x over previous
; __device__ __forceinline__ unsigned xb_ld(unsigned* p)              { return __hip_atomic_load(p, __ATOMIC_RELAXED, __HIP_MEMORY_SCOPE_AGENT); }
; __device__ __forceinline__ unsigned xb_add(unsigned* p, unsigned v) { return __hip_atomic_fetch_add(p, v, __ATOMIC_RELAXED, __HIP_MEMORY_SCOPE_AGENT); }
; #define XB_SPIN(cond, bar) do { unsigned _sp = 0; while (cond) { __builtin_amdgcn_s_sleep(1); \
;     if ((++_sp & 255u) == 0u) { if (xb_ld(&(bar)[XB_TMO])) break; if (_sp > XB_SPIN_CAP) { atomicAdd(&(bar)[XB_TMO], 1u); break; } } } } while (0)
; __device__ __forceinline__ void xcd_barrier(const XcdBarrier& b) {
;     ...
;         unsigned nloc = b.st[0], nx = b.st[1];
;         if (nloc == 0u) { xcd_barrier_complete(bar, b.x, nloc, nx); b.st[0] = nloc; b.st[1] = nx; }
;         const unsigned old = xb_add(&bar[XB_XSUB(b.x)], 1u);
;         const unsigned gen = old / nloc;
;         if (old + 1u == (gen + 1u) * nloc) {
;             __builtin_amdgcn_fence(__ATOMIC_RELEASE, "agent");
;             asm volatile("s_waitcnt vmcnt(0)" ::: "memory");
;             const unsigned og = xb_add(&bar[XB_TOP], 1u);
;             const unsigned tg = og / nx;
;             if (og + 1u == (tg + 1u) * nx) xb_add(&bar[XB_TOPGEN], 1u);
;             else XB_SPIN(xb_ld(&bar[XB_TOPGEN]) == tg, bar);
;             __builtin_amdgcn_fence(__ATOMIC_ACQUIRE, "agent");
;             xb_add(&bar[XB_XGEN(b.x)], 1u);
;             asm volatile("s_waitcnt vmcnt(0)" ::: "memory");
;         } else {
;             XB_SPIN(xb_ld(&bar[XB_XGEN(b.x)]) == gen, bar);
.Lxs0_105:
	s_or_b64 exec, exec, s[6:7]
	v_cvt_f32_u32_e32 v4, v2
	s_waitcnt vmcnt(0)
	v_readfirstlane_b32 s4, v3
	v_sub_u32_e32 v3, 0, v2
	v_rcp_iflag_f32_e32 v4, v4
	v_add_u32_e32 v5, s4, v0
	v_mul_f32_e32 v4, 0x4f7ffffe, v4
	v_cvt_u32_f32_e32 v4, v4
	v_mul_lo_u32 v0, v3, v4
	v_mul_hi_u32 v0, v4, v0
	v_add_u32_e32 v0, v4, v0
	v_mul_hi_u32 v0, v5, v0
	v_mul_lo_u32 v3, v0, v2
	v_sub_u32_e32 v3, v5, v3
	v_add_u32_e32 v4, 1, v0
	v_cmp_ge_u32_e32 vcc, v3, v2
	s_nop 1
	v_cndmask_b32_e32 v0, v0, v4, vcc
	v_sub_u32_e32 v4, v3, v2
	v_cndmask_b32_e32 v3, v3, v4, vcc
	v_add_u32_e32 v4, 1, v0
	v_cmp_ge_u32_e32 vcc, v3, v2
	v_add_u32_e32 v3, 1, v5
	s_nop 0
	v_cndmask_b32_e32 v0, v0, v4, vcc
	v_mul_lo_u32 v4, v2, v0
	v_add_u32_e32 v2, v4, v2
	v_cmp_ne_u32_e32 vcc, v3, v2
	s_and_saveexec_b64 s[4:5], vcc
	s_xor_b64 s[4:5], exec, s[4:5]
	s_cbranch_execz .Lxs0_119
	s_waitcnt lgkmcnt(0)
	buffer_inv sc1
	v_sub_u32_e32 v1, v3, v4
	v_cmp_eq_u32_e32 vcc, 1, v1
	s_cbranch_vccz .Lewb_1
	buffer_wbl2 sc1
.Lewb_1:
	v_mov_b32_e32 v1, 0x2000
	global_load_dword v1, v1, s[2:3] offset:1024 sc1
	s_add_u32 s10, s2, 0x2400
	s_addc_u32 s11, s3, 0
	s_waitcnt vmcnt(0)
	v_cmp_eq_u32_e32 vcc, v1, v0
	s_and_saveexec_b64 s[6:7], vcc
	s_cbranch_execz .Lxs0_118
	v_readlane_b32 s12, v228, 2
	v_readlane_b32 s18, v228, 8
	v_readlane_b32 s13, v228, 3
	v_readlane_b32 s19, v228, 9
	s_add_u32 s8, s18, 0x179ed200
	v_readlane_b32 s14, v228, 4
	v_readlane_b32 s15, v228, 5
	s_addc_u32 s9, s19, 0
	s_mov_b32 s22, 1
	s_mov_b64 s[12:13], 0
	v_mov_b32_e32 v1, 0
	v_readlane_b32 s16, v228, 6
	v_readlane_b32 s17, v228, 7
	s_branch .Lxs0_109

; __device__ __forceinline__ unsigned xb_ld(unsigned* p)              { return __hip_atomic_load(p, __ATOMIC_RELAXED, __HIP_MEMORY_SCOPE_AGENT); }
; __device__ __forceinline__ unsigned xb_add(unsigned* p, unsigned v) { return __hip_atomic_fetch_add(p, v, __ATOMIC_RELAXED, __HIP_MEMORY_SCOPE_AGENT); }
; #define XB_SPIN(cond, bar) do { unsigned _sp = 0; while (cond) { __builtin_amdgcn_s_sleep(1); \
;     if ((++_sp & 255u) == 0u) { if (xb_ld(&(bar)[XB_TMO])) break; if (_sp > XB_SPIN_CAP) { atomicAdd(&(bar)[XB_TMO], 1u); break; } } } } while (0)
; __device__ __forceinline__ void xcd_barrier(const XcdBarrier& b) {
;     ...
;         unsigned nloc = b.st[0], nx = b.st[1];
;         if (nloc == 0u) { xcd_barrier_complete(bar, b.x, nloc, nx); b.st[0] = nloc; b.st[1] = nx; }
;         const unsigned old = xb_add(&bar[XB_XSUB(b.x)], 1u);
;         const unsigned gen = old / nloc;
;         if (old + 1u == (gen + 1u) * nloc) {
;             __builtin_amdgcn_fence(__ATOMIC_RELEASE, "agent");
;             asm volatile("s_waitcnt vmcnt(0)" ::: "memory");
;             const unsigned og = xb_add(&bar[XB_TOP], 1u);
;             const unsigned tg = og / nx;
;             if (og + 1u == (tg + 1u) * nx) xb_add(&bar[XB_TOPGEN], 1u);
;             else XB_SPIN(xb_ld(&bar[XB_TOPGEN]) == tg, bar);
;             __builtin_amdgcn_fence(__ATOMIC_ACQUIRE, "agent");
;             xb_add(&bar[XB_XGEN(b.x)], 1u);
;             asm volatile("s_waitcnt vmcnt(0)" ::: "memory");
;         } else {
;             XB_SPIN(xb_ld(&bar[XB_XGEN(b.x)]) == gen, bar);
.LBB0_942:
	s_or_b64 exec, exec, s[6:7]
	v_cvt_f32_u32_e32 v4, v2
	s_waitcnt vmcnt(0)
	v_readfirstlane_b32 s4, v3
	v_sub_u32_e32 v3, 0, v2
	v_rcp_iflag_f32_e32 v4, v4
	v_add_u32_e32 v5, s4, v1
	v_mul_f32_e32 v4, 0x4f7ffffe, v4
	v_cvt_u32_f32_e32 v4, v4
	v_mul_lo_u32 v1, v3, v4
	v_mul_hi_u32 v1, v4, v1
	v_add_u32_e32 v1, v4, v1
	v_mul_hi_u32 v1, v5, v1
	v_mul_lo_u32 v3, v1, v2
	v_sub_u32_e32 v3, v5, v3
	v_add_u32_e32 v4, 1, v1
	v_cmp_ge_u32_e32 vcc, v3, v2
	s_nop 1
	v_cndmask_b32_e32 v1, v1, v4, vcc
	v_sub_u32_e32 v4, v3, v2
	v_cndmask_b32_e32 v3, v3, v4, vcc
	v_add_u32_e32 v4, 1, v1
	v_cmp_ge_u32_e32 vcc, v3, v2
	v_add_u32_e32 v3, 1, v5
	s_nop 0
	v_cndmask_b32_e32 v1, v1, v4, vcc
	v_mul_lo_u32 v4, v2, v1
	v_add_u32_e32 v2, v4, v2
	v_cmp_ne_u32_e32 vcc, v3, v2
	s_and_saveexec_b64 s[4:5], vcc
	s_xor_b64 s[4:5], exec, s[4:5]
	s_cbranch_execz .LBB0_956
	s_waitcnt lgkmcnt(0)
	buffer_inv sc1
	v_sub_u32_e32 v0, v3, v4
	v_cmp_eq_u32_e32 vcc, 1, v0
	s_cbranch_vccz .Lewb_9
	buffer_wbl2 sc1
.Lewb_9:
	v_mov_b32_e32 v0, 0x2000
	global_load_dword v0, v0, s[2:3] offset:1024 sc1
	s_add_u32 s10, s2, 0x2400
	s_addc_u32 s11, s3, 0
	s_waitcnt vmcnt(0)
	v_cmp_eq_u32_e32 vcc, v0, v1
	s_and_saveexec_b64 s[6:7], vcc
	s_cbranch_execz .LBB0_955
	v_readlane_b32 s12, v228, 2
	v_readlane_b32 s18, v228, 8
	v_readlane_b32 s13, v228, 3
	v_readlane_b32 s19, v228, 9
	s_add_u32 s8, s18, 0x179ed200
	v_readlane_b32 s14, v228, 4
	v_readlane_b32 s15, v228, 5
	s_addc_u32 s9, s19, 0
	s_mov_b32 s22, 1
	s_mov_b64 s[12:13], 0
	v_mov_b32_e32 v0, 0
	v_readlane_b32 s16, v228, 6
	v_readlane_b32 s17, v228, 7
	s_branch .LBB0_946

; __device__ __forceinline__ unsigned xb_ld(unsigned* p)              { return __hip_atomic_load(p, __ATOMIC_RELAXED, __HIP_MEMORY_SCOPE_AGENT); }
; #define XB_SPIN(cond, bar) do { unsigned _sp = 0; while (cond) { __builtin_amdgcn_s_sleep(1); \
;     if ((++_sp & 255u) == 0u) { if (xb_ld(&(bar)[XB_TMO])) break; if (_sp > XB_SPIN_CAP) { atomicAdd(&(bar)[XB_TMO], 1u); break; } } } } while (0)
; __device__ __forceinline__ void xcd_barrier(const XcdBarrier& b) {
;     ...
;         } else {
;             XB_SPIN(xb_ld(&bar[XB_XGEN(b.x)]) == gen, bar);
.Lewb_13:
	v_mov_b32_e32 v1, 0x2000
	global_load_dword v1, v1, s[2:3] offset:1024 sc1
	s_add_u32 s10, s2, 0x2400
	s_addc_u32 s11, s3, 0
	s_waitcnt vmcnt(0)
	v_cmp_eq_u32_e32 vcc, v1, v0
	s_and_saveexec_b64 s[6:7], vcc
	s_cbranch_execz .LBB0_1207
	v_readlane_b32 s12, v228, 2
	v_readlane_b32 s14, v228, 4
	v_readlane_b32 s15, v228, 5
	v_readlane_b32 s18, v228, 8
	v_readlane_b32 s19, v228, 9
	s_mov_b64 s[14:15], s[18:19]
	v_readlane_b32 s13, v228, 3
	s_add_u32 s8, s14, 0x179ed200
	s_addc_u32 s9, s15, 0
	s_mov_b32 s22, 1
	s_mov_b64 s[12:13], 0
	v_mov_b32_e32 v1, 0
	v_readlane_b32 s16, v228, 6
	v_readlane_b32 s17, v228, 7
	s_branch .LBB0_1198
